# stronger conversion rebalancing on top of the live fixes: 3840 (layers 1-2) / 1792 (layer 0) next-layer items in the FFN-up idle half round
# baseline (speedup 1.0000x reference)
; __device__ __forceinline__ PItem p0_decode(const Args& a, int it) {
;     constexpr int I_IN = 16 * 96, I_OUT = 16 * 32, I_W1 = 16 * 88, I_W2 = 44 * 32, I_LAYER = I_IN + I_OUT + 2 * I_W1 + I_W2;
;     const int l = it / I_LAYER, e = l >> 1, odd = l & 1; int r = it % I_LAYER;
;     unsigned char* wl = a.ws + WS_W + (size_t)l * W_LAYER; float* cv = (float*)(a.ws + WS_CVEC) + (size_t)l * CVEC_LAYER;
;     PItem p;
;     if (r < I_IN) { const int kb = r / 96, nb = r % 96; p.W = (odd ? a.in[13] : a.in[5]) + (size_t)e * D * EIN; p.N = EIN; p.K = D; p.g = l > 0 ? a.in[21] + (size_t)(l - 1) * D : nullptr; p.be = l > 0 ? a.in[22] + (size_t)(l - 1) * D : nullptr;
;         p.WT = (bf16*)(wl + W_IN); p.drow0 = in_dst_row(32 * nb, odd); p.k0 = 64 * kb; p.n0 = 32 * nb; p.c1 = cv; p.c2 = cv + EIN; return p; } r -= I_IN;
;     if (r < I_OUT) { const int kb = r / 32, nb = r % 32; p.W = (odd ? a.in[15] : a.in[6]) + (size_t)e * D * D; p.N = D; p.K = D; p.g = nullptr; p.be = nullptr;
;         p.WT = (bf16*)(wl + W_OUT); p.drow0 = 32 * nb; p.k0 = 64 * kb; p.n0 = 32 * nb; p.c1 = nullptr; p.c2 = nullptr; return p; } r -= I_OUT;
;     if (r < 2 * I_W1) { const int second = r >= I_W1; if (second) r -= I_W1; const int kb = r / 88, nb = r % 88, n0 = 32 * nb; p.W = (second ? a.in[17] : a.in[16]) + (size_t)l * D * DFF; p.N = DFF; p.K = D;
;         p.g = a.in[19] + (size_t)l * D; p.be = a.in[20] + (size_t)l * D; p.WT = (bf16*)(wl + W_13); p.drow0 = 256 * (n0 >> 7) + (second ? 128 : 0) + (n0 & 127); p.k0 = 64 * kb; p.n0 = n0; p.c1 = cv + 2 * EIN; p.c2 = cv + 2 * EIN + NUP; return p; } r -= 2 * I_W1;
; __global__ void __launch_bounds__(NWAVES * 64, 2) mk_fwd(Args args) {
;     ...
;             if (F.G == 256 && (int)blockIdx.x >= 128) { const int wi = (int)blockIdx.x - 128;
;                 if (l == 0) p_convert_tail(F, args, P_ILAYER - P_IW2, P_ILAYER, wi, 128);
;                 if (l < 3) { const int xs = (l == 0) ? 768 : 1792; p_convert_tail(F, args, (l + 2) * P_ILAYER - xs, (l + 2) * P_ILAYER, wi, 128); } }
.LBB0_1294:
	v_readlane_b32 s0, v255, 62
	s_cmp_eq_u32 s0, 3
	v_readlane_b32 s1, v255, 63
	s_cbranch_scc1 .LBB0_1348
	v_readlane_b32 s0, v255, 53
	v_readlane_b32 s1, v255, 54
	s_and_b64 s[0:1], s[0:1], exec
	v_readlane_b32 s10, v255, 62
	s_movk_i32 s0, 0xf900
	s_mul_i32 s7, s10, 0x1880
	s_cselect_b32 s0, s0, 0xfffff100
	s_addk_i32 s7, 0x3100
	v_readlane_b32 s1, v253, 59
	s_add_i32 s1, s1, s7
	v_mbcnt_lo_u32_b32 v0, -1, 0
	v_mbcnt_hi_u32_b32 v0, -1, v0
	s_add_i32 s13, s1, s0
	v_add_u32_e32 v0, s75, v0
	s_cmp_ge_i32 s13, s7
	v_readlane_b32 s11, v255, 63
	s_cbranch_scc1 .LBB0_1348
	s_mul_hi_i32 s0, s13, 0x5397829d
	s_lshr_b32 s1, s0, 31
	s_ashr_i32 s0, s0, 11
	s_add_i32 s30, s0, s1
	s_mul_i32 s1, s30, 0x1880
	s_ashr_i32 s34, s30, 1
	s_and_b32 s0, s30, 1
	s_sub_i32 s1, s13, s1
	s_ashr_i32 s31, s30, 31
	s_mul_i32 s10, s30, 0x1880000
	v_readlane_b32 s11, v253, 5
	s_mul_hi_i32 s2, s30, 0x1880000
	s_add_u32 s22, s11, s10
	v_readlane_b32 s10, v253, 6
	s_addc_u32 s23, s10, s2
	s_mul_i32 s10, s30, 0x11000
	v_readlane_b32 s11, v253, 7
	s_mul_hi_i32 s2, s30, 0x11000
	s_add_u32 s26, s11, s10
	v_readlane_b32 s10, v253, 8
	s_addc_u32 s27, s10, s2
	s_cmpk_gt_i32 s1, 0x5ff
	s_mov_b64 s[48:49], -1
	s_cbranch_scc0 .LBB0_1305
	s_cmpk_gt_u32 s1, 0x7ff
	s_cbranch_scc0 .LBB0_1302
	s_mov_b64 s[18:19], -1
	s_cmpk_gt_u32 s1, 0x12ff
	s_mul_hi_i32 s2, s30, 0xb00000
	s_mul_i32 s17, s30, 0xb00000
	s_cbranch_scc0 .LBB0_1300
	v_readlane_b32 s56, v253, 26
	v_readlane_b32 s57, v253, 27
	s_add_u32 s10, s56, s17
	s_addc_u32 s11, s57, s2
	s_add_u32 s14, s22, 0x1300000
	s_addc_u32 s15, s23, 0
	s_lshl_b32 s16, s1, 1
	s_lshl_b32 s12, s1, 5
	s_and_b32 s16, s16, 0x7fffffc0
	v_readlane_b32 s58, v253, 28
	v_readlane_b32 s59, v253, 29
	v_readlane_b32 s60, v253, 30
	v_readlane_b32 s61, v253, 31
	v_readlane_b32 s62, v253, 32
	v_readlane_b32 s63, v253, 33
	s_and_b32 s12, s12, 0x3e0
	s_addk_i32 s16, 0xda00
	s_mov_b64 s[18:19], 0

; __device__ __forceinline__ PItem p0_decode(const Args& a, int it) {
;     constexpr int I_IN = 16 * 96, I_OUT = 16 * 32, I_W1 = 16 * 88, I_W2 = 44 * 32, I_LAYER = I_IN + I_OUT + 2 * I_W1 + I_W2;
;     const int l = it / I_LAYER, e = l >> 1, odd = l & 1; int r = it % I_LAYER;
;     unsigned char* wl = a.ws + WS_W + (size_t)l * W_LAYER; float* cv = (float*)(a.ws + WS_CVEC) + (size_t)l * CVEC_LAYER;
;     PItem p;
;     if (r < I_IN) { const int kb = r / 96, nb = r % 96; p.W = (odd ? a.in[13] : a.in[5]) + (size_t)e * D * EIN; p.N = EIN; p.K = D; p.g = l > 0 ? a.in[21] + (size_t)(l - 1) * D : nullptr; p.be = l > 0 ? a.in[22] + (size_t)(l - 1) * D : nullptr;
;         p.WT = (bf16*)(wl + W_IN); p.drow0 = in_dst_row(32 * nb, odd); p.k0 = 64 * kb; p.n0 = 32 * nb; p.c1 = cv; p.c2 = cv + EIN; return p; } r -= I_IN;
;     if (r < I_OUT) { const int kb = r / 32, nb = r % 32; p.W = (odd ? a.in[15] : a.in[6]) + (size_t)e * D * D; p.N = D; p.K = D; p.g = nullptr; p.be = nullptr;
;         p.WT = (bf16*)(wl + W_OUT); p.drow0 = 32 * nb; p.k0 = 64 * kb; p.n0 = 32 * nb; p.c1 = nullptr; p.c2 = nullptr; return p; } r -= I_OUT;
;     if (r < 2 * I_W1) { const int second = r >= I_W1; if (second) r -= I_W1; const int kb = r / 88, nb = r % 88, n0 = 32 * nb; p.W = (second ? a.in[17] : a.in[16]) + (size_t)l * D * DFF; p.N = DFF; p.K = D;
; __global__ void __launch_bounds__(NWAVES * 64, 2) mk_fwd(Args args) {
;     ...
;                 { int Gq = F.G; asm volatile("" : "+s"(Gq)); const int nmu = g.N >> 5, mfirst = (nmu <= Gq / 2 || Gq < 256) ? (Gq - nmu > 0 ? Gq - nmu : 0) : Gq / 2; for (int mu = (int)blockIdx.x - mfirst; mu >= 0 && mu < nmu; mu += Gq - mfirst) pg8::mini_ring(F.lds + RING_OFF, g.A, g.Bt, g.K, E, mu, F.wave);
;                   if (l < 3) { if (mfirst > 0) { if ((int)blockIdx.x < mfirst) { p_convert_tail(F, args, (l + 1) * P_ILAYER, (l + 2) * P_ILAYER - ((F.G == 256) ? (l == 0 ? 768 : 1792) : 0), (int)blockIdx.x, mfirst); if (l == 0) p_state_copies_tail(F, args, (int)blockIdx.x, mfirst); } }
;                   else { p_convert_tail(F, args, (l + 1) * P_ILAYER, (l + 2) * P_ILAYER - ((F.G == 256) ? (l == 0 ? 768 : 1792) : 0), (int)blockIdx.x, F.G); if (l == 0) p_state_copies_tail(F, args, (int)blockIdx.x, F.G); } } } }
.LBB0_1546:
	s_waitcnt vmcnt(24)
	s_barrier
	v_readlane_b32 s0, v255, 62
	s_cmp_lg_u32 s0, 3
	s_mov_b64 s[10:11], -1
	v_readlane_b32 s1, v255, 63
	s_cmp_lt_i32 s29, 33
	s_cbranch_scc0 .LBB0_1627
	v_readlane_b32 s0, v255, 62
	v_readlane_b32 s1, v255, 63
	s_mul_i32 s2, s0, 0x1880
	v_readlane_b32 s0, v255, 53
	v_readlane_b32 s1, v255, 54
	s_and_b64 s[0:1], s[0:1], exec
	s_movk_i32 s0, 0xf900
	s_cselect_b32 s7, s0, 0xfffff100
	v_readlane_b32 s0, v252, 62
	v_readlane_b32 s1, v252, 63
	s_and_b64 s[0:1], s[0:1], exec
	s_cselect_b32 s0, s7, 0
	s_add_i32 s7, s2, s0
	v_readlane_b32 s0, v253, 60
	s_addk_i32 s7, 0x3100
	v_mbcnt_lo_u32_b32 v0, -1, 0
	v_mbcnt_hi_u32_b32 v0, -1, v0
	s_add_i32 s29, s0, s2
	v_add_u32_e32 v0, s75, v0
	s_cmp_ge_i32 s29, s7
	s_cbranch_scc1 .LBB0_1601
	s_mul_hi_i32 s0, s29, 0x5397829d
	s_lshr_b32 s1, s0, 31
	s_ashr_i32 s0, s0, 11
	s_add_i32 s26, s0, s1
	s_mul_i32 s1, s26, 0x1880
	s_ashr_i32 s30, s26, 1
	s_and_b32 s0, s26, 1
	s_sub_i32 s1, s29, s1
	s_ashr_i32 s27, s26, 31
	s_mul_i32 s10, s26, 0x1880000
	v_readlane_b32 s11, v253, 5
	s_mul_hi_i32 s2, s26, 0x1880000
	s_add_u32 s22, s11, s10
	v_readlane_b32 s10, v253, 6
	s_addc_u32 s23, s10, s2
	s_mul_i32 s10, s26, 0x11000
	v_readlane_b32 s11, v253, 7
	s_mul_hi_i32 s2, s26, 0x11000
	s_add_u32 s24, s11, s10
	v_readlane_b32 s10, v253, 8
	s_addc_u32 s25, s10, s2
	s_cmpk_gt_i32 s1, 0x5ff
	s_mov_b64 s[46:47], -1
	s_cbranch_scc0 .LBB0_1558
	s_cmpk_gt_u32 s1, 0x7ff
	s_cbranch_scc0 .LBB0_1555
	s_mov_b64 s[18:19], -1
	s_cmpk_gt_u32 s1, 0x12ff
	s_mul_hi_i32 s2, s26, 0xb00000
	s_mul_i32 s13, s26, 0xb00000
	s_cbranch_scc0 .LBB0_1553
	v_readlane_b32 s56, v253, 26
	v_readlane_b32 s57, v253, 27
	s_add_u32 s10, s56, s13
	s_addc_u32 s11, s57, s2
	s_add_u32 s14, s22, 0x1300000
	s_addc_u32 s15, s23, 0
	s_lshl_b32 s16, s1, 1
	s_lshl_b32 s12, s1, 5
	s_and_b32 s16, s16, 0x7fffffc0
	v_readlane_b32 s58, v253, 28
	v_readlane_b32 s59, v253, 29
	v_readlane_b32 s60, v253, 30
	v_readlane_b32 s61, v253, 31
	v_readlane_b32 s62, v253, 32
	v_readlane_b32 s63, v253, 33
	s_and_b32 s12, s12, 0x3e0
	s_addk_i32 s16, 0xda00
	s_mov_b64 s[18:19], 0

; __device__ __forceinline__ PItem p0_decode(const Args& a, int it) {
;     constexpr int I_IN = 16 * 96, I_OUT = 16 * 32, I_W1 = 16 * 88, I_W2 = 44 * 32, I_LAYER = I_IN + I_OUT + 2 * I_W1 + I_W2;
;     const int l = it / I_LAYER, e = l >> 1, odd = l & 1; int r = it % I_LAYER;
;     unsigned char* wl = a.ws + WS_W + (size_t)l * W_LAYER; float* cv = (float*)(a.ws + WS_CVEC) + (size_t)l * CVEC_LAYER;
;     PItem p;
;     if (r < I_IN) { const int kb = r / 96, nb = r % 96; p.W = (odd ? a.in[13] : a.in[5]) + (size_t)e * D * EIN; p.N = EIN; p.K = D; p.g = l > 0 ? a.in[21] + (size_t)(l - 1) * D : nullptr; p.be = l > 0 ? a.in[22] + (size_t)(l - 1) * D : nullptr;
;         p.WT = (bf16*)(wl + W_IN); p.drow0 = in_dst_row(32 * nb, odd); p.k0 = 64 * kb; p.n0 = 32 * nb; p.c1 = cv; p.c2 = cv + EIN; return p; } r -= I_IN;
;     if (r < I_OUT) { const int kb = r / 32, nb = r % 32; p.W = (odd ? a.in[15] : a.in[6]) + (size_t)e * D * D; p.N = D; p.K = D; p.g = nullptr; p.be = nullptr;
;         p.WT = (bf16*)(wl + W_OUT); p.drow0 = 32 * nb; p.k0 = 64 * kb; p.n0 = 32 * nb; p.c1 = nullptr; p.c2 = nullptr; return p; } r -= I_OUT;
;     if (r < 2 * I_W1) { const int second = r >= I_W1; if (second) r -= I_W1; const int kb = r / 88, nb = r % 88, n0 = 32 * nb; p.W = (second ? a.in[17] : a.in[16]) + (size_t)l * D * DFF; p.N = DFF; p.K = D;
; __global__ void __launch_bounds__(NWAVES * 64, 2) mk_fwd(Args args) {
;     ...
;                 { int Gq = F.G; asm volatile("" : "+s"(Gq)); const int nmu = g.N >> 5, mfirst = (nmu <= Gq / 2 || Gq < 256) ? (Gq - nmu > 0 ? Gq - nmu : 0) : Gq / 2; for (int mu = (int)blockIdx.x - mfirst; mu >= 0 && mu < nmu; mu += Gq - mfirst) pg8::mini_ring(F.lds + RING_OFF, g.A, g.Bt, g.K, E, mu, F.wave);
;                   if (l < 3) { if (mfirst > 0) { if ((int)blockIdx.x < mfirst) { p_convert_tail(F, args, (l + 1) * P_ILAYER, (l + 2) * P_ILAYER - ((F.G == 256) ? (l == 0 ? 768 : 1792) : 0), (int)blockIdx.x, mfirst); if (l == 0) p_state_copies_tail(F, args, (int)blockIdx.x, mfirst); } }
;                   else { p_convert_tail(F, args, (l + 1) * P_ILAYER, (l + 2) * P_ILAYER - ((F.G == 256) ? (l == 0 ? 768 : 1792) : 0), (int)blockIdx.x, F.G); if (l == 0) p_state_copies_tail(F, args, (int)blockIdx.x, F.G); } } } }
.LBB0_1627:
	s_and_b64 vcc, exec, s[10:11]
	s_cbranch_vccz .LBB0_1707
	v_readlane_b32 s0, v254, 27
	s_cmp_ge_i32 s0, s28
	v_readlane_b32 s1, v254, 28
	s_cbranch_scc1 .LBB0_1707
	v_readlane_b32 s0, v255, 62
	s_cmp_eq_u32 s0, 3
	s_cbranch_scc1 .LBB0_1682
	v_readlane_b32 s0, v255, 62
	v_readlane_b32 s1, v255, 63
	s_mul_i32 s2, s0, 0x1880
	v_readlane_b32 s0, v255, 53
	v_readlane_b32 s1, v255, 54
	s_and_b64 s[0:1], s[0:1], exec
	s_movk_i32 s0, 0xf900
	s_cselect_b32 s7, s0, 0xfffff100
	v_readlane_b32 s0, v252, 62
	v_readlane_b32 s1, v252, 63
	s_and_b64 s[0:1], s[0:1], exec
	s_cselect_b32 s0, s7, 0
	s_add_i32 s7, s2, s0
	v_readlane_b32 s0, v253, 60
	s_addk_i32 s7, 0x3100
	v_mbcnt_lo_u32_b32 v0, -1, 0
	v_mbcnt_hi_u32_b32 v0, -1, v0
	s_add_i32 s29, s0, s2
	v_add_u32_e32 v0, s75, v0
	s_cmp_ge_i32 s29, s7
	s_cbranch_scc1 .LBB0_1682
	s_mul_hi_i32 s0, s29, 0x5397829d
	s_lshr_b32 s1, s0, 31
	s_ashr_i32 s0, s0, 11
	s_add_i32 s26, s0, s1
	s_mul_i32 s1, s26, 0x1880
	s_ashr_i32 s30, s26, 1
	s_and_b32 s0, s26, 1
	s_sub_i32 s1, s29, s1
	s_ashr_i32 s27, s26, 31
	s_mul_i32 s10, s26, 0x1880000
	v_readlane_b32 s11, v253, 5
	s_mul_hi_i32 s2, s26, 0x1880000
	s_add_u32 s22, s11, s10
	v_readlane_b32 s10, v253, 6
	s_addc_u32 s23, s10, s2
	s_mul_i32 s10, s26, 0x11000
	v_readlane_b32 s11, v253, 7
	s_mul_hi_i32 s2, s26, 0x11000
	s_add_u32 s24, s11, s10
	v_readlane_b32 s10, v253, 8
	s_addc_u32 s25, s10, s2
	v_readlane_b32 s48, v250, 0
	s_cmpk_gt_i32 s1, 0x5ff
	s_mov_b64 s[46:47], -1
	v_readlane_b32 s49, v250, 1
	s_cbranch_scc0 .LBB0_1639
	s_cmpk_gt_u32 s1, 0x7ff
	s_cbranch_scc0 .LBB0_1636
	s_mov_b64 s[18:19], -1
	s_cmpk_gt_u32 s1, 0x12ff
	s_mul_hi_i32 s2, s26, 0xb00000
	s_mul_i32 s13, s26, 0xb00000
	s_cbranch_scc0 .LBB0_1634
	v_readlane_b32 s56, v253, 26
	v_readlane_b32 s57, v253, 27
	s_add_u32 s10, s56, s13
	s_addc_u32 s11, s57, s2
	s_add_u32 s14, s22, 0x1300000
	s_addc_u32 s15, s23, 0
	s_lshl_b32 s16, s1, 1
	s_lshl_b32 s12, s1, 5
	s_and_b32 s16, s16, 0x7fffffc0
	v_readlane_b32 s58, v253, 28
	v_readlane_b32 s59, v253, 29
	v_readlane_b32 s60, v253, 30
	v_readlane_b32 s61, v253, 31
	v_readlane_b32 s62, v253, 32
	v_readlane_b32 s63, v253, 33
	s_and_b32 s12, s12, 0x3e0
	s_addk_i32 s16, 0xda00
	s_mov_b64 s[18:19], 0
